# v12: forwarded 87 redundant VGPR copies (left by the packed-f32 split) into their uses; each dead v_mov became s_nop 0 to keep wait-state distances
# speedup vs baseline: 1.0096x; 1.0022x over previous
; __device__ __forceinline__ unsigned cvtpk(float lo, float hi) { f32x2 v = {lo, hi}; bf16x2_t b = __builtin_convertvector(v, bf16x2_t); return *(unsigned*)&b; }
; __device__ __forceinline__ void fin_row(const float* mod, const f32x4 (&g4)[4], int lane, const RowX& r, float (&h)[16]) {
;   float ss = 0.f;
; #pragma unroll
;   for (int i = 0; i < 4; ++i) ss += r.v[i][0] * r.v[i][0] + r.v[i][1] * r.v[i][1] + r.v[i][2] * r.v[i][2] + r.v[i][3] * r.v[i][3];
;   ss = wave_sum(ss);
;   const float rstd = rsqrtf(ss * (1.f / 1024.f) + 1e-6f);
;   const float* m = mod + r.bi * 3072;
; #pragma unroll
;   for (int i = 0; i < 4; ++i) {
;     const int c = i * 256 + lane * 4;
;     const f32x4 sh = *(const f32x4*)(m + c), sc = *(const f32x4*)(m + 1024 + c);
; #pragma unroll
;     for (int e = 0; e < 4; ++e) {
;       const float hv = r.v[i][e] * rstd * g4[i][e] * (1.f + sc[e]) + sh[e];
;       h[4 * i + e] = __uint_as_float(cvtpk(hv, 0.f) << 16);
;     }
;   }
; }
; __device__ void phase_norm_lerp(const Params& p, const float* mod) {
;     ...
;   if (r0 > 0) { ld_row(p, r0 - 1, lane, xc); }
;   ld_row(p, r0, lane, xa);
;   if (r0 + 1 < NTOK) ld_row(p, r0 + 1, lane, xb);
;   if (r0 > 0) fin_row(mod, g4, lane, xc, hp);
;   else {
; #pragma unroll
;     for (int e = 0; e < 16; ++e) hp[e] = 0.f;
;   }
;   fin_row(mod, g4, lane, xa, hc);
.LBB0_48:
	s_or_saveexec_b64 s[4:5], s[4:5]
	v_mov_b32_e32 v191, 0
	v_mov_b32_e32 v196, 0
	v_mov_b32_e32 v197, 0
	v_mov_b32_e32 v194, 0
	v_mov_b32_e32 v195, 0
	v_mov_b32_e32 v200, 0
	v_mov_b32_e32 v201, 0
	v_mov_b32_e32 v198, 0
	v_mov_b32_e32 v199, 0
	v_mov_b32_e32 v204, 0
	v_mov_b32_e32 v205, 0
	v_mov_b32_e32 v202, 0
	v_mov_b32_e32 v203, 0
	v_mov_b32_e32 v214, 0
	v_mov_b32_e32 v215, 0
	v_mov_b32_e32 v212, 0
	v_mov_b32_e32 v213, 0
	s_xor_b64 exec, exec, s[4:5]
	s_cbranch_execz .LBB0_50
	s_waitcnt vmcnt(6)
	s_nop 0
	s_nop 0
	s_nop 0
	s_nop 0
	v_mul_f32_e64 v132, v85, v85
	v_mul_f32_e64 v133, v81, v81
	s_waitcnt vmcnt(4)
	s_nop 0
	v_fma_f32 v130, v84, v84, v132
	v_fma_f32 v131, v80, v80, v133
	s_nop 0
	s_nop 0
	v_fma_f32 v130, v86, v86, v130
	v_fma_f32 v131, v82, v82, v131
	s_nop 0
	s_nop 0
	s_nop 0
	v_fma_f32 v130, v87, v87, v130
	v_fma_f32 v131, v83, v83, v131
	s_nop 0
	s_nop 0
	v_mul_f32_e64 v134, v93, v93
	v_mul_f32_e64 v135, v89, v89
	v_add_f32_e32 v130, v130, v131
	v_fma_f32 v132, v92, v92, v134
	v_fma_f32 v133, v88, v88, v135
	s_nop 0
	s_nop 0
	v_fma_f32 v132, v94, v94, v132
	v_fma_f32 v133, v90, v90, v133
	s_nop 0
	v_mov_b32_e32 v135, v91
	v_fma_f32 v132, v95, v95, v132
	v_fma_f32 v133, v135, v135, v133
	s_movk_i32 s0, 0xc00
	v_add_f32_e32 v130, v133, v130
	v_add_f32_e32 v134, v132, v130
	v_mbcnt_lo_u32_b32 v130, -1, 0
	v_mbcnt_hi_u32_b32 v137, -1, v130
	v_and_b32_e32 v130, 64, v137
	v_add_u32_e32 v138, 64, v130
	v_xor_b32_e32 v139, 32, v137
	v_cmp_lt_i32_e32 vcc, v139, v138
	v_xor_b32_e32 v140, 16, v137
	v_xor_b32_e32 v141, 8, v137
	v_cndmask_b32_e32 v130, v137, v139, vcc
	v_lshlrev_b32_e32 v130, 2, v130
	ds_bpermute_b32 v135, v130, v134
	v_mul_lo_u32 v130, v181, s0
	v_ashrrev_i32_e32 v131, 31, v130
	v_lshl_add_u64 v[132:133], v[130:131], 2, s[38:39]
	s_mov_b64 s[0:1], 0x1000
	v_lshl_add_u64 v[168:169], v[132:133], 0, s[0:1]
	v_mov_b32_e32 v131, 0
	v_mov_b32_e32 v130, v190
	v_lshl_add_u64 v[172:173], v[132:133], 0, v[130:131]
	v_lshl_add_u64 v[132:133], v[168:169], 0, v[130:131]
	v_cmp_lt_i32_e32 vcc, v140, v138
	global_load_dwordx4 v[144:147], v[132:133], off
	global_load_dwordx4 v[148:151], v[172:173], off
	v_cndmask_b32_e32 v132, v137, v140, vcc
	s_waitcnt lgkmcnt(0)
	v_add_f32_e32 v130, v134, v135
	v_lshlrev_b32_e32 v132, 2, v132
	ds_bpermute_b32 v132, v132, v130
	v_cmp_lt_i32_e32 vcc, v141, v138
	v_mov_b32_e32 v133, v131
	v_xor_b32_e32 v142, 4, v137
	v_xor_b32_e32 v143, 2, v137
	s_waitcnt lgkmcnt(0)
	v_add_f32_e32 v134, v130, v132
	v_cndmask_b32_e32 v130, v137, v141, vcc
	v_lshlrev_b32_e32 v130, 2, v130
	ds_bpermute_b32 v135, v130, v134
	v_or_b32_e32 v130, 0x100, v136
	v_lshlrev_b32_e32 v132, 2, v130
	v_lshl_add_u64 v[132:133], v[168:169], 0, v[132:133]
	v_cmp_lt_i32_e32 vcc, v142, v138
	global_load_dwordx4 v[152:155], v[132:133], off
	global_load_dwordx4 v[156:159], v[172:173], off offset:1024
	v_cndmask_b32_e32 v133, v137, v142, vcc
	s_waitcnt lgkmcnt(0)
	v_add_f32_e32 v132, v134, v135
	v_lshlrev_b32_e32 v133, 2, v133
	ds_bpermute_b32 v133, v133, v132
	v_cmp_lt_i32_e32 vcc, v143, v138
	v_mov_b32_e32 v135, v131
	v_xor_b32_e32 v193, 1, v137
	s_mov_b32 s0, 0x800000
	s_waitcnt lgkmcnt(0)
	v_add_f32_e32 v133, v132, v133
	v_cndmask_b32_e32 v132, v137, v143, vcc
	v_lshlrev_b32_e32 v132, 2, v132
	ds_bpermute_b32 v170, v132, v133
	v_or_b32_e32 v132, 0x200, v136
	v_lshlrev_b32_e32 v134, 2, v132
	v_lshl_add_u64 v[134:135], v[168:169], 0, v[134:135]
	v_cmp_lt_i32_e32 vcc, v193, v138
	global_load_dwordx4 v[160:163], v[134:135], off
	global_load_dwordx4 v[164:167], v[172:173], off offset:2048
	v_cndmask_b32_e32 v134, v137, v193, vcc
	s_waitcnt lgkmcnt(0)
	v_add_f32_e32 v133, v133, v170
	v_lshlrev_b32_e32 v134, 2, v134
	ds_bpermute_b32 v134, v134, v133
	v_mov_b32_e32 v171, v131
	s_waitcnt lgkmcnt(0)
	v_add_f32_e32 v133, v133, v134
	v_mov_b32_e32 v134, 0x358637bd
	v_fmac_f32_e32 v134, 0x3a800000, v133
	v_mul_f32_e32 v133, 0x4b800000, v134
	v_cmp_gt_f32_e32 vcc, s0, v134
	s_nop 1
	v_cndmask_b32_e32 v133, v134, v133, vcc
	v_or_b32_e32 v134, 0x300, v136
	v_lshlrev_b32_e32 v170, 2, v134
	v_lshl_add_u64 v[168:169], v[168:169], 0, v[170:171]
	global_load_dwordx4 v[168:171], v[168:169], off
	s_nop 0
	global_load_dwordx4 v[172:175], v[172:173], off offset:3072
	v_rsq_f32_e32 v133, v133
	s_nop 0
	v_mul_f32_e32 v135, 0x45800000, v133
	v_cndmask_b32_e32 v136, v133, v135, vcc
	v_mul_f32_e32 v133, v80, v136
	v_mul_f32_e32 v133, v0, v133
	s_waitcnt vmcnt(7)
	v_add_f32_e32 v135, 1.0, v144
	s_waitcnt vmcnt(6)
	v_fma_f32 v133, v135, v133, v148
	v_mul_f32_e32 v135, v81, v136
	v_mul_f32_e32 v135, v1, v135
	v_add_f32_e32 v144, 1.0, v145
	v_cvt_pk_bf16_f32 v133, v133, 0
	v_fma_f32 v135, v144, v135, v149
	v_cvt_pk_bf16_f32 v135, v135, 0
	v_lshlrev_b32_e32 v194, 16, v133
	v_mul_f32_e32 v133, v82, v136
	v_lshlrev_b32_e32 v195, 16, v135
	v_mul_f32_e32 v133, v2, v133
	v_add_f32_e32 v135, 1.0, v146
	v_fma_f32 v133, v135, v133, v150
	v_mul_f32_e32 v135, v83, v136
	v_mul_f32_e32 v135, v3, v135
	v_add_f32_e32 v144, 1.0, v147
	v_cvt_pk_bf16_f32 v133, v133, 0
	v_fmac_f32_e32 v151, v144, v135
	v_cvt_pk_bf16_f32 v135, v151, 0
	v_lshlrev_b32_e32 v196, 16, v133
	v_mul_f32_e32 v133, v84, v136
	v_lshlrev_b32_e32 v197, 16, v135
	v_mul_f32_e32 v133, v56, v133
	s_waitcnt vmcnt(5)
	v_add_f32_e32 v135, 1.0, v152
	s_waitcnt vmcnt(4)
	v_fma_f32 v133, v135, v133, v156
	v_mul_f32_e32 v135, v85, v136
	v_mul_f32_e32 v135, v57, v135
	v_add_f32_e32 v144, 1.0, v153
	v_cvt_pk_bf16_f32 v133, v133, 0
	v_fma_f32 v135, v144, v135, v157
	v_cvt_pk_bf16_f32 v135, v135, 0
	v_lshlrev_b32_e32 v198, 16, v133
	v_mul_f32_e32 v133, v86, v136
	v_lshlrev_b32_e32 v199, 16, v135
	v_mul_f32_e32 v133, v58, v133
	v_add_f32_e32 v135, 1.0, v154
	v_fma_f32 v133, v135, v133, v158
	v_mul_f32_e32 v135, v87, v136
	v_mul_f32_e32 v135, v59, v135
	v_add_f32_e32 v144, 1.0, v155
	v_fmac_f32_e32 v159, v144, v135
	v_cvt_pk_bf16_f32 v135, v159, 0
	v_lshlrev_b32_e32 v201, 16, v135
	v_mul_f32_e32 v135, v88, v136
	v_mul_f32_e32 v135, v64, v135
	s_waitcnt vmcnt(3)
; __device__ __forceinline__ unsigned cvtpk(float lo, float hi) { f32x2 v = {lo, hi}; bf16x2_t b = __builtin_convertvector(v, bf16x2_t); return *(unsigned*)&b; }
; __device__ __forceinline__ void fin_row(const float* mod, const f32x4 (&g4)[4], int lane, const RowX& r, float (&h)[16]) {
;   float ss = 0.f;
; #pragma unroll
;   for (int i = 0; i < 4; ++i) ss += r.v[i][0] * r.v[i][0] + r.v[i][1] * r.v[i][1] + r.v[i][2] * r.v[i][2] + r.v[i][3] * r.v[i][3];
;   ss = wave_sum(ss);
;   const float rstd = rsqrtf(ss * (1.f / 1024.f) + 1e-6f);
;   const float* m = mod + r.bi * 3072;
; #pragma unroll
;   for (int i = 0; i < 4; ++i) {
;     const int c = i * 256 + lane * 4;
;     const f32x4 sh = *(const f32x4*)(m + c), sc = *(const f32x4*)(m + 1024 + c);
; #pragma unroll
;     for (int e = 0; e < 4; ++e) {
;       const float hv = r.v[i][e] * rstd * g4[i][e] * (1.f + sc[e]) + sh[e];
;       h[4 * i + e] = __uint_as_float(cvtpk(hv, 0.f) << 16);
;     }
;   }
; }
; __device__ void phase_norm_lerp(const Params& p, const float* mod) {
;     ...
;   if (r0 > 0) { ld_row(p, r0 - 1, lane, xc); }
;   ld_row(p, r0, lane, xa);
;   if (r0 + 1 < NTOK) ld_row(p, r0 + 1, lane, xb);
;   if (r0 > 0) fin_row(mod, g4, lane, xc, hp);
;   else {
; #pragma unroll
;     for (int e = 0; e < 16; ++e) hp[e] = 0.f;
;   }
;   fin_row(mod, g4, lane, xa, hc);
;   xa = xb;
;   if (r0 + 2 < NTOK) ld_row(p, r0 + 2, lane, xb);
	v_add_f32_e32 v144, 1.0, v160
	s_waitcnt vmcnt(2)
	v_fma_f32 v135, v144, v135, v164
	v_mul_f32_e32 v144, v89, v136
	v_mul_f32_e32 v144, v65, v144
	v_add_f32_e32 v145, 1.0, v161
	v_cvt_pk_bf16_f32 v135, v135, 0
	v_fma_f32 v144, v145, v144, v165
	v_cvt_pk_bf16_f32 v144, v144, 0
	v_lshlrev_b32_e32 v202, 16, v135
	v_mul_f32_e32 v135, v90, v136
	v_lshlrev_b32_e32 v203, 16, v144
	v_mul_f32_e32 v135, v66, v135
	v_add_f32_e32 v144, 1.0, v162
	v_fma_f32 v135, v144, v135, v166
	v_mul_f32_e32 v144, v91, v136
	v_mul_f32_e32 v144, v67, v144
	v_add_f32_e32 v145, 1.0, v163
	v_fmac_f32_e32 v167, v145, v144
	v_cvt_pk_bf16_f32 v144, v167, 0
	v_lshlrev_b32_e32 v205, 16, v144
	v_mul_f32_e32 v144, v92, v136
	v_mul_f32_e32 v144, v72, v144
	s_waitcnt vmcnt(1)
	v_add_f32_e32 v145, 1.0, v168
	s_waitcnt vmcnt(0)
	v_fma_f32 v144, v145, v144, v172
	v_mul_f32_e32 v145, v93, v136
	v_mul_f32_e32 v145, v73, v145
	v_add_f32_e32 v146, 1.0, v169
	v_cvt_pk_bf16_f32 v144, v144, 0
	v_fma_f32 v145, v146, v145, v173
	v_cvt_pk_bf16_f32 v145, v145, 0
	v_lshlrev_b32_e32 v212, 16, v144
	v_mul_f32_e32 v144, v94, v136
	v_lshlrev_b32_e32 v213, 16, v145
	v_mul_f32_e32 v144, v74, v144
	v_add_f32_e32 v145, 1.0, v170
	v_mul_f32_e32 v136, v95, v136
	v_fma_f32 v144, v145, v144, v174
	v_mul_f32_e32 v136, v75, v136
	v_add_f32_e32 v145, 1.0, v171
	v_fmac_f32_e32 v175, v145, v136
	v_cvt_pk_bf16_f32 v133, v133, 0
	v_cvt_pk_bf16_f32 v135, v135, 0
	v_cvt_pk_bf16_f32 v144, v144, 0
	v_cvt_pk_bf16_f32 v136, v175, 0
	v_lshlrev_b32_e32 v200, 16, v133
	v_mov_b32_e32 v133, v131
	v_lshlrev_b32_e32 v204, 16, v135
	v_mov_b32_e32 v135, v131
	v_lshlrev_b32_e32 v214, 16, v144
	v_lshlrev_b32_e32 v215, 16, v136
.LBB0_50:
	s_or_b64 exec, exec, s[4:5]
	v_lshl_add_u64 v[128:129], v[128:129], 2, s[38:39]
	s_mov_b64 s[0:1], 0x1000
	v_lshlrev_b64 v[206:207], 2, v[130:131]
	v_lshl_add_u64 v[144:145], v[128:129], 0, s[0:1]
	v_lshl_add_u64 v[146:147], v[128:129], 0, v[190:191]
	v_lshl_add_u64 v[130:131], v[128:129], 0, v[206:207]
	v_lshlrev_b64 v[208:209], 2, v[132:133]
	v_lshlrev_b64 v[210:211], 2, v[134:135]
	v_lshl_add_u64 v[148:149], v[144:145], 0, v[190:191]
	global_load_dwordx4 v[168:171], v[146:147], off
	global_load_dwordx4 v[172:175], v[148:149], off
	v_lshl_add_u64 v[146:147], v[144:145], 0, v[206:207]
	global_load_dwordx4 v[160:163], v[130:131], off
	global_load_dwordx4 v[164:167], v[146:147], off
	v_lshl_add_u64 v[130:131], v[128:129], 0, v[208:209]
	v_lshl_add_u64 v[128:129], v[128:129], 0, v[210:211]
	v_lshl_add_u64 v[132:133], v[144:145], 0, v[208:209]
	global_load_dwordx4 v[152:155], v[130:131], off
	global_load_dwordx4 v[156:159], v[132:133], off
	v_lshl_add_u64 v[130:131], v[144:145], 0, v[210:211]
	global_load_dwordx4 v[144:147], v[128:129], off
	global_load_dwordx4 v[148:151], v[130:131], off
	s_waitcnt vmcnt(11)
	v_mov_b32_e32 v218, v125
	s_waitcnt vmcnt(10)
	v_mov_b32_e32 v219, v121
	v_mov_b32_e32 v216, v124
	v_mov_b32_e32 v217, v120
	v_mul_f32_e64 v128, v218, v218
	v_mul_f32_e64 v129, v219, v219
	s_nop 0
	v_fma_f32 v128, v216, v216, v128
	v_fma_f32 v129, v217, v217, v129
	s_nop 0
	v_fma_f32 v128, v126, v126, v128
	v_fma_f32 v129, v122, v122, v129
	s_nop 0
	s_nop 0
	s_waitcnt vmcnt(9)
	s_nop 0
	s_waitcnt vmcnt(8)
	s_nop 0
	v_fma_f32 v128, v127, v127, v128
	v_fma_f32 v129, v123, v123, v129
	s_nop 0
	s_nop 0
	v_mul_f32_e64 v132, v117, v117
	v_mul_f32_e64 v133, v113, v113
	v_add_f32_e32 v128, v128, v129
	v_fma_f32 v130, v116, v116, v132
	v_fma_f32 v131, v112, v112, v133
	s_nop 0
	s_nop 0
	v_fma_f32 v130, v118, v118, v130
	v_fma_f32 v131, v114, v114, v131
	v_mov_b32_e32 v132, v119
	v_mov_b32_e32 v133, v115
	v_fma_f32 v130, v132, v132, v130
	v_fma_f32 v131, v133, v133, v131
	v_cmp_lt_i32_e32 vcc, v139, v138
	v_add_f32_e32 v128, v128, v130
	v_add_f32_e32 v128, v128, v131
	v_cndmask_b32_e32 v129, v137, v139, vcc
	v_lshlrev_b32_e32 v185, 2, v129
	ds_bpermute_b32 v129, v185, v128
	v_cmp_lt_i32_e32 vcc, v140, v138
	s_mov_b32 s0, 0x107fe
	v_mov_b64_e32 v[134:135], v[106:107]
	v_mov_b64_e32 v[132:133], v[104:105]
	s_waitcnt lgkmcnt(0)
	v_add_f32_e32 v128, v128, v129
	v_cndmask_b32_e32 v129, v137, v140, vcc
	v_lshlrev_b32_e32 v187, 2, v129
	ds_bpermute_b32 v129, v187, v128
	v_cmp_lt_i32_e32 vcc, v141, v138
	v_mov_b32_e32 v223, v183
	s_waitcnt lgkmcnt(0)
	v_add_f32_e32 v128, v128, v129
	v_cndmask_b32_e32 v129, v137, v141, vcc
	v_lshlrev_b32_e32 v189, 2, v129
	ds_bpermute_b32 v129, v189, v128
	v_cmp_lt_i32_e32 vcc, v142, v138
	s_waitcnt lgkmcnt(0)
	v_add_f32_e32 v128, v128, v129
	v_cndmask_b32_e32 v129, v137, v142, vcc
	v_lshlrev_b32_e32 v218, 2, v129
	ds_bpermute_b32 v129, v218, v128
	v_cmp_lt_i32_e32 vcc, v143, v138
	s_waitcnt lgkmcnt(0)
	v_add_f32_e32 v128, v128, v129
	v_cndmask_b32_e32 v129, v137, v143, vcc
	v_lshlrev_b32_e32 v219, 2, v129
	ds_bpermute_b32 v129, v219, v128
	v_cmp_lt_i32_e32 vcc, v193, v138
	v_mov_b64_e32 v[142:143], v[98:99]
	v_mov_b64_e32 v[140:141], v[96:97]
	s_waitcnt lgkmcnt(0)
	v_add_f32_e32 v216, v128, v129
	v_cndmask_b32_e32 v128, v137, v193, vcc
	v_lshlrev_b32_e32 v220, 2, v128
	ds_bpermute_b32 v193, v220, v216
	v_mov_b64_e32 v[130:131], v[110:111]
	v_mov_b64_e32 v[138:139], v[102:103]
	v_cmp_gt_i32_e32 vcc, s0, v192
	v_mov_b64_e32 v[128:129], v[108:109]
	v_mov_b64_e32 v[136:137], v[100:101]
	s_and_saveexec_b64 s[4:5], vcc
	s_cbranch_execz .LBB0_56
	v_add_u32_e32 v129, 2, v192
	s_mov_b32 s0, 0x3e0f83e1
	v_mul_hi_i32 v128, v129, s0
	v_lshrrev_b32_e32 v130, 31, v128
	v_ashrrev_i32_e32 v128, 11, v128
	v_add_u32_e32 v128, v128, v130
	s_movk_i32 s0, 0xdf00
	v_mad_i32_i24 v130, v128, s0, v129
	s_movk_i32 s0, 0x1fff
	v_cmp_lt_i32_e32 vcc, s0, v130
	v_mov_b64_e32 v[132:133], s[36:37]
	s_and_saveexec_b64 s[0:1], vcc
	s_xor_b64 s[6:7], exec, s[0:1]
	v_add_u32_e32 v130, 0xffffe000, v130
	v_mov_b32_e32 v131, 0
	v_mov_b64_e32 v[132:133], s[40:41]
	s_or_saveexec_b64 s[6:7], s[6:7]
	v_mov_b32_e32 v223, 8
	v_mov_b64_e32 v[134:135], 20
	s_xor_b64 exec, exec, s[6:7]
	v_ashrrev_i32_e32 v131, 31, v130
	v_mov_b64_e32 v[134:135], 25
	v_mov_b32_e32 v223, v128
	s_or_b64 exec, exec, s[6:7]
	v_ashrrev_i32_e32 v129, 31, v128
	v_lshlrev_b64 v[128:129], v134, v[128:129]
	v_lshl_add_u64 v[128:129], v[132:133], 0, v[128:129]
	v_lshlrev_b64 v[130:131], 12, v[130:131]
	v_lshl_add_u64 v[128:129], v[128:129], 0, v[130:131]
	v_mov_b32_e32 v191, 0
	v_lshl_add_u64 v[140:141], v[128:129], 0, v[190:191]
	global_load_dwordx4 v[128:131], v[140:141], off
	global_load_dwordx4 v[132:135], v[140:141], off offset:1024
	global_load_dwordx4 v[136:139], v[140:141], off offset:2048
	s_nop 0
	global_load_dwordx4 v[140:143], v[140:141], off offset:3072

; __device__ __forceinline__ unsigned cvtpk(float lo, float hi) { f32x2 v = {lo, hi}; bf16x2_t b = __builtin_convertvector(v, bf16x2_t); return *(unsigned*)&b; }
; __device__ __forceinline__ void fin_row(const float* mod, const f32x4 (&g4)[4], int lane, const RowX& r, float (&h)[16]) {
;   float ss = 0.f;
; #pragma unroll
;   for (int i = 0; i < 4; ++i) ss += r.v[i][0] * r.v[i][0] + r.v[i][1] * r.v[i][1] + r.v[i][2] * r.v[i][2] + r.v[i][3] * r.v[i][3];
;   ss = wave_sum(ss);
;   const float rstd = rsqrtf(ss * (1.f / 1024.f) + 1e-6f);
;   const float* m = mod + r.bi * 3072;
; #pragma unroll
;   for (int i = 0; i < 4; ++i) {
;     const int c = i * 256 + lane * 4;
;     const f32x4 sh = *(const f32x4*)(m + c), sc = *(const f32x4*)(m + 1024 + c);
; #pragma unroll
;     for (int e = 0; e < 4; ++e) {
;       const float hv = r.v[i][e] * rstd * g4[i][e] * (1.f + sc[e]) + sh[e];
;       h[4 * i + e] = __uint_as_float(cvtpk(hv, 0.f) << 16);
;     }
;   }
; }
; __device__ void phase_norm_lerp(const Params& p, const float* mod) {
;     ...
;   for (int n = r0; n < r1; ++n) {
;     const int t = n % TL;
;     if (n + 3 < NTOK) ld_row(p, n + 3, lane, xc);
;     if (n + 1 < NTOK) fin_row(mod, g4, lane, xa, hn);
;     else {
; #pragma unroll
;       for (int e = 0; e < 16; ++e) hn[e] = 0.f;
;     }
.LBB0_64:
	s_or_b64 exec, exec, s[4:5]
	v_mov_b32_e32 v216, 0
	v_cmp_gt_i32_e32 vcc, s22, v128
	v_mov_b32_e32 v217, v216
	v_mov_b32_e32 v174, v216
	v_mov_b32_e32 v175, v216
	v_mov_b32_e32 v172, v216
	v_mov_b32_e32 v173, v216
	v_mov_b32_e32 v166, v216
	v_mov_b32_e32 v167, v216
	v_mov_b32_e32 v162, v216
	v_mov_b32_e32 v163, v216
	v_mov_b32_e32 v164, v216
	v_mov_b32_e32 v165, v216
	v_mov_b32_e32 v170, v216
	v_mov_b32_e32 v171, v216
	v_mov_b32_e32 v168, v216
	v_mov_b32_e32 v169, v216
	s_and_saveexec_b64 s[4:5], vcc
	s_cbranch_execz .LBB0_57
	s_nop 0
	s_nop 0
	s_nop 0
	s_nop 0
	v_mul_f32_e64 v132, v109, v109
	v_mul_f32_e64 v133, v105, v105
	s_nop 0
	v_fma_f32 v130, v108, v108, v132
	v_fma_f32 v131, v104, v104, v133
	v_mov_b32_e32 v132, v110
	v_mov_b32_e32 v133, v106
	v_fma_f32 v138, v132, v132, v130
	v_fma_f32 v139, v133, v133, v131
	s_nop 0
	s_nop 0
	s_nop 0
	v_fma_f32 v138, v111, v111, v138
	v_fma_f32 v139, v107, v107, v139
	s_nop 0
	s_nop 0
	v_mul_f32_e64 v164, v97, v97
	v_mul_f32_e64 v165, v101, v101
	v_add_f32_e32 v129, v138, v139
	v_fma_f32 v140, v96, v96, v164
	v_fma_f32 v141, v100, v100, v165
	s_nop 0
	s_nop 0
	v_fma_f32 v140, v98, v98, v140
	v_fma_f32 v141, v102, v102, v141
	v_mov_b32_e32 v164, v99
	v_mov_b32_e32 v165, v103
	v_fma_f32 v168, v164, v164, v140
	v_fma_f32 v169, v165, v165, v141
	v_mul_lo_u32 v130, v183, s23
	v_add_f32_e32 v129, v169, v129
	v_add_f32_e32 v129, v168, v129
	ds_bpermute_b32 v168, v185, v129
	v_ashrrev_i32_e32 v131, 31, v130
	v_lshl_add_u64 v[142:143], v[130:131], 2, s[38:39]
	v_lshl_add_u64 v[162:163], v[142:143], 0, s[12:13]
	v_lshl_add_u64 v[130:131], v[142:143], 0, v[190:191]
	s_waitcnt lgkmcnt(0)
	v_add_f32_e32 v129, v129, v168
	ds_bpermute_b32 v168, v187, v129
	v_lshl_add_u64 v[134:135], v[162:163], 0, v[190:191]
	global_load_dwordx4 v[130:133], v[130:131], off
	s_nop 0
	global_load_dwordx4 v[134:137], v[134:135], off
	v_lshl_add_u64 v[138:139], v[142:143], 0, v[206:207]
	v_lshl_add_u64 v[164:165], v[162:163], 0, v[206:207]
	global_load_dwordx4 v[138:141], v[138:139], off
	s_nop 0
	global_load_dwordx4 v[164:167], v[164:165], off
	s_waitcnt lgkmcnt(0)
	v_add_f32_e32 v129, v129, v168
	ds_bpermute_b32 v168, v189, v129
	v_lshl_add_u64 v[170:171], v[162:163], 0, v[208:209]
	v_lshl_add_u64 v[162:163], v[162:163], 0, v[210:211]
	s_waitcnt lgkmcnt(0)
	v_add_f32_e32 v129, v129, v168
	v_lshl_add_u64 v[168:169], v[142:143], 0, v[208:209]
	global_load_dwordx4 v[172:175], v[168:169], off
	global_load_dwordx4 v[224:227], v[170:171], off
	v_lshl_add_u64 v[142:143], v[142:143], 0, v[210:211]
	global_load_dwordx4 v[228:231], v[162:163], off
	global_load_dwordx4 v[232:235], v[142:143], off
	ds_bpermute_b32 v168, v218, v129
	s_waitcnt lgkmcnt(0)
	v_add_f32_e32 v129, v129, v168
	ds_bpermute_b32 v168, v219, v129
	s_waitcnt lgkmcnt(0)
	v_add_f32_e32 v129, v129, v168
	ds_bpermute_b32 v168, v220, v129
	s_waitcnt lgkmcnt(0)
	v_add_f32_e32 v129, v129, v168
	v_fmamk_f32 v129, v129, 0x3a800000, v221
	v_mul_f32_e32 v168, 0x4b800000, v129
	v_cmp_gt_f32_e32 vcc, s0, v129
	s_waitcnt vmcnt(6)
	v_add_f32_e32 v134, 1.0, v134
	v_cndmask_b32_e32 v129, v129, v168, vcc
	v_rsq_f32_e32 v129, v129
	v_add_f32_e32 v135, 1.0, v135
	v_add_f32_e32 v136, 1.0, v136
	v_add_f32_e32 v137, 1.0, v137
	v_mul_f32_e32 v142, 0x45800000, v129
	v_cndmask_b32_e32 v129, v129, v142, vcc
	v_mul_f32_e32 v108, v108, v129
	v_mul_f32_e32 v108, v0, v108
	v_fma_f32 v108, v134, v108, v130
	v_cvt_pk_bf16_f32 v108, v108, 0
	v_mul_f32_e32 v104, v104, v129
	v_lshlrev_b32_e32 v169, 16, v108
	v_mul_f32_e32 v104, v56, v104
	s_waitcnt vmcnt(4)
	v_add_f32_e32 v108, 1.0, v164
	v_mul_f32_e32 v105, v105, v129
	v_fma_f32 v104, v108, v104, v138
	v_mul_f32_e32 v105, v57, v105
	v_add_f32_e32 v108, 1.0, v165
	v_cvt_pk_bf16_f32 v104, v104, 0
	v_fma_f32 v105, v108, v105, v139
	v_cvt_pk_bf16_f32 v105, v105, 0
	v_lshlrev_b32_e32 v165, 16, v104
	v_mul_f32_e32 v104, v106, v129
	v_lshlrev_b32_e32 v164, 16, v105
	v_mul_f32_e32 v104, v58, v104
	v_add_f32_e32 v105, 1.0, v166
	v_fma_f32 v104, v105, v104, v140
	v_cvt_pk_bf16_f32 v104, v104, 0
	v_mul_f32_e32 v100, v100, v129
	v_lshlrev_b32_e32 v163, 16, v104
	v_mul_f32_e32 v100, v64, v100
	s_waitcnt vmcnt(2)
	v_add_f32_e32 v104, 1.0, v224
	v_mul_f32_e32 v101, v101, v129
	v_fma_f32 v100, v104, v100, v172
	v_mul_f32_e32 v101, v65, v101
	v_add_f32_e32 v104, 1.0, v225
	v_cvt_pk_bf16_f32 v100, v100, 0
	v_fma_f32 v101, v104, v101, v173
	v_add_f32_e32 v106, 1.0, v167
	v_cvt_pk_bf16_f32 v101, v101, 0
	v_lshlrev_b32_e32 v167, 16, v100
	v_mul_f32_e32 v100, v102, v129
	v_lshlrev_b32_e32 v166, 16, v101
	v_mul_f32_e32 v100, v66, v100
	v_add_f32_e32 v101, 1.0, v226
	v_fma_f32 v100, v101, v100, v174
	v_cvt_pk_bf16_f32 v100, v100, 0
	v_mul_f32_e32 v96, v96, v129
	v_mul_f32_e32 v101, v103, v129
	v_lshlrev_b32_e32 v173, 16, v100
	v_mul_f32_e32 v96, v72, v96
	s_waitcnt vmcnt(1)
	v_add_f32_e32 v100, 1.0, v228
	v_mul_f32_e32 v97, v97, v129
	v_mul_f32_e32 v101, v67, v101
	v_add_f32_e32 v102, 1.0, v227
	s_waitcnt vmcnt(0)
	v_fma_f32 v96, v100, v96, v232
	v_mul_f32_e32 v97, v73, v97
	v_add_f32_e32 v100, 1.0, v229
	v_fmac_f32_e32 v175, v102, v101
	v_cvt_pk_bf16_f32 v96, v96, 0
	v_fma_f32 v97, v100, v97, v233
	v_cvt_pk_bf16_f32 v101, v175, 0
	v_cvt_pk_bf16_f32 v97, v97, 0
	v_lshlrev_b32_e32 v175, 16, v96
	v_mul_f32_e32 v96, v98, v129
	v_lshlrev_b32_e32 v174, 16, v97
	v_mul_f32_e32 v96, v74, v96
	v_add_f32_e32 v97, 1.0, v230
	v_mul_f32_e32 v109, v109, v129
	v_mul_f32_e32 v110, v110, v129
	v_mul_f32_e32 v111, v111, v129
	v_mul_f32_e32 v105, v107, v129
	v_fma_f32 v96, v97, v96, v234
	v_mul_f32_e32 v97, v99, v129
	v_mul_f32_e32 v109, v1, v109
	v_mul_f32_e32 v110, v2, v110
	v_mul_f32_e32 v111, v3, v111
	v_mul_f32_e32 v105, v59, v105
	v_mul_f32_e32 v97, v75, v97
	v_add_f32_e32 v98, 1.0, v231
	v_fma_f32 v109, v135, v109, v131
	v_fma_f32 v110, v136, v110, v132
	v_fmac_f32_e32 v133, v137, v111
	v_fmac_f32_e32 v141, v106, v105
	v_fmac_f32_e32 v235, v98, v97
	v_cvt_pk_bf16_f32 v109, v109, 0
	v_cvt_pk_bf16_f32 v110, v110, 0
	v_cvt_pk_bf16_f32 v111, v133, 0
	v_cvt_pk_bf16_f32 v105, v141, 0
	v_cvt_pk_bf16_f32 v96, v96, 0
	v_cvt_pk_bf16_f32 v97, v235, 0
	v_lshlrev_b32_e32 v168, 16, v109
	v_lshlrev_b32_e32 v170, 16, v111
	v_lshlrev_b32_e32 v171, 16, v110
	v_lshlrev_b32_e32 v162, 16, v105
	v_lshlrev_b32_e32 v172, 16, v101
	v_lshlrev_b32_e32 v216, 16, v97
	v_lshlrev_b32_e32 v217, 16, v96
	s_branch .LBB0_57

; __device__ void phase_scan(const Params& p, char* lds) {
;     ...
;         const float inv = rsqrtf(fmaxf(ss, 1e-24f));
; #pragma unroll
;         for (int e = 0; e < 8; ++e) kk[e] *= inv;
;       };
;       auto stageB = [&](int c) {
;         char* buf = lds + (c & 1) * SC_BUF;
;         const f32x4 i0 = *(const f32x4*)(IC + pstep * 64 + j0), i1 = *(const f32x4*)(IC + pstep * 64 + j0 + 4);
;         const float ic[8] = {i0[0], i0[1], i0[2], i0[3], i1[0], i1[1], i1[2], i1[3]};
;         const float* Pt = (const float*)(buf + SC_P) + pstep * 64 + j0;
;         const f32x4 pt0 = *(const f32x4*)(Pt), pt1 = *(const f32x4*)(Pt + 4);
;         f32x4 pm0 = {1.f, 1.f, 1.f, 1.f}, pm1 = pm0;
;         if (pstep > 0) { pm0 = *(const f32x4*)(Pt - 64); pm1 = *(const f32x4*)(Pt - 60); }
;         const float pt[8] = {pt0[0], pt0[1], pt0[2], pt0[3], pt1[0], pt1[1], pt1[2], pt1[3]};
;         const float pm[8] = {pm0[0], pm0[1], pm0[2], pm0[3], pm1[0], pm1[1], pm1[2], pm1[3]};
;         const u32x4 an = {cvtpk(-kk[0] * pm[0], -kk[1] * pm[1]), cvtpk(-kk[2] * pm[2], -kk[3] * pm[3]), cvtpk(-kk[4] * pm[4], -kk[5] * pm[5]), cvtpk(-kk[6] * pm[6], -kk[7] * pm[7])};
;         const u32x4 rn = {cvtpk(rr[0] * pt[0], rr[1] * pt[1]), cvtpk(rr[2] * pt[2], rr[3] * pt[3]), cvtpk(rr[4] * pt[4], rr[5] * pt[5]), cvtpk(rr[6] * pt[6], rr[7] * pt[7])};
;         bf16_t* ARa = (bf16_t*)(buf + SC_ARA) + (pblk * 4 + psb) * 64; bf16_t* ARr = (bf16_t*)(buf + SC_ARR) + (pblk * 4 + psb) * 64;
;         { u32x2 lo = {an[0], an[1]}, hi2 = {an[2], an[3]}; *(u32x2*)(ARa + apos0) = lo; *(u32x2*)(ARa + apos1) = hi2; }
;         { u32x2 lo = {rn[0], rn[1]}, hi2 = {rn[2], rn[3]}; *(u32x2*)(ARr + apos0) = lo; *(u32x2*)(ARr + apos1) = hi2; }
;         *(u32x4*)(SCR + (pstep * 4 + 0) * 64 + j0) = an; *(u32x4*)(SCR + (pstep * 4 + 1) * 64 + j0) = rn;
;         float bs = 0.f;
;         unsigned bq[8], kq[8];
;         unsigned* BK = (unsigned*)(buf + SC_BK) + (pblk * 64 + j0) * 4 + psb;
; #pragma unroll
;         for (int e = 0; e < 8; ++e) {
;           const float kd = kr[e] * (1.f + (ic[e] - 1.f) * kac[e]);
;           const float ip = __builtin_amdgcn_rcpf(pt[e]);
;           const unsigned pr2 = cvtpk(kk[e] * ic[e] * ip, kd * ip);
;           BK[e * 4] = pr2;
;           bq[e] = pr2 & 0xffffu; kq[e] = pr2 >> 16;
;           bs += rr[e] * kd * rkc[e];
;         }
.LBB0_498:
	s_or_b64 exec, exec, s[80:81]
	v_add_f32_e32 v101, v101, v120
	v_max_f32_e32 v101, 0x179abe15, v101
	v_rsq_f32_e32 v120, v101
	v_lshlrev_b32_e32 v122, 16, v58
	v_and_b32_e32 v123, 0xffff0000, v58
	v_lshlrev_b32_e32 v124, 16, v59
	v_mul_f32_e64 v112, v112, v120
	v_mul_f32_e64 v113, v113, v120
	v_mul_f32_e64 v114, v114, v120
	v_mul_f32_e64 v115, v115, v120
	v_and_b32_e32 v125, 0xffff0000, v59
	v_lshlrev_b32_e32 v126, 16, v60
	v_and_b32_e32 v127, 0xffff0000, v60
	v_lshlrev_b32_e32 v128, 16, v61
	v_and_b32_e32 v129, 0xffff0000, v61
	v_mul_f32_e64 v116, v116, v120
	v_mul_f32_e64 v117, v117, v120
	v_mul_f32_e64 v118, v118, v120
	v_mul_f32_e64 v119, v119, v120
	s_waitcnt lgkmcnt(1)
	v_mul_f32_e64 v58, v82, -v112
	v_mul_f32_e64 v59, v83, -v113
	v_mul_f32_e64 v60, v84, -v114
	v_mul_f32_e64 v61, v85, -v115
	v_cvt_pk_bf16_f32 v58, v58, v59
	v_cvt_pk_bf16_f32 v59, v60, v61
	s_waitcnt lgkmcnt(0)
	v_mul_f32_e64 v60, v78, -v116
	v_mul_f32_e64 v61, v79, -v117
	v_mul_f32_e64 v78, v80, -v118
	v_mul_f32_e64 v79, v81, -v119
	v_cvt_pk_bf16_f32 v60, v60, v61
	v_cvt_pk_bf16_f32 v61, v78, v79
	v_mul_f32_e64 v78, v74, v122
	v_mul_f32_e64 v79, v75, v123
	v_mul_f32_e64 v80, v76, v124
	v_mul_f32_e64 v81, v77, v125
	v_cvt_pk_bf16_f32 v78, v78, v79
	v_cvt_pk_bf16_f32 v79, v80, v81
	v_mul_f32_e64 v80, v8, v126
	v_mul_f32_e64 v81, v9, v127
	v_mul_f32_e64 v82, v10, v128
	v_mul_f32_e64 v83, v11, v129
	v_cvt_pk_bf16_f32 v80, v80, v81
	v_cvt_pk_bf16_f32 v81, v82, v83
	v_add_u32_e32 v82, 0x2000, v194
	ds_write2_b64 v82, v[58:59], v[60:61] offset1:2
	v_add_u32_e32 v82, 0x3000, v194
	ds_write2_b64 v82, v[78:79], v[80:81] offset1:2
	ds_write_b128 v195, v[58:61]
	ds_write_b128 v195, v[78:81] offset:128
	v_add_f32_e32 v58, -1.0, v12
	v_fma_f32 v59, v22, v58, 1.0
	v_rcp_f32_e32 v60, v74
	s_nop 0
	s_nop 0
	v_mov_b32_e32 v79, v110
	v_mul_f32_e64 v58, v12, v112
	v_mul_f32_e64 v59, v59, v79
	v_mov_b32_e32 v110, v113
	v_mul_f32_e32 v12, v59, v122
	v_fma_f32 v79, v30, v12, 0
	v_add_f32_e32 v12, -1.0, v13
	v_mul_f32_e64 v61, v59, v60
	v_mul_f32_e64 v60, v58, v60
	v_fma_f32 v59, v23, v12, 1.0
	v_rcp_f32_e32 v12, v75
	s_nop 0
	v_mul_f32_e64 v58, v13, v110
	v_mul_f32_e64 v59, v59, v111
	v_cvt_pk_bf16_f32 v60, v60, v61
	v_mul_f32_e64 v13, v59, v12
	v_mul_f32_e64 v12, v58, v12
	v_rcp_f32_e32 v58, v76
	v_cvt_pk_bf16_f32 v75, v12, v13
	v_mul_f32_e32 v12, v59, v123
	v_add_u32_e32 v80, 0x4000, v198
	v_fmac_f32_e32 v79, v31, v12
	v_add_f32_e32 v12, -1.0, v14
	v_and_b32_e32 v74, 0xffff, v60
	v_lshrrev_b32_e32 v78, 16, v60
	ds_write2_b32 v80, v60, v75 offset1:4
	v_fma_f32 v13, v24, v12, 1.0
	s_nop 0
	s_nop 0
	v_mov_b32_e32 v61, v108
	v_mul_f32_e64 v12, v14, v114
	v_mul_f32_e64 v13, v13, v61
	v_rcp_f32_e32 v14, v77
	v_mul_f32_e64 v59, v13, v58
	v_mul_f32_e64 v58, v12, v58
	v_mul_f32_e32 v12, v13, v124
	v_fmac_f32_e32 v79, v32, v12
	v_add_f32_e32 v12, -1.0, v15
	v_fma_f32 v13, v25, v12, 1.0
	s_nop 0
	v_mov_b32_e32 v108, v115
	v_mul_f32_e64 v12, v15, v108
	v_mul_f32_e64 v13, v13, v109
	v_rcp_f32_e32 v8, v8
	v_mul_f32_e64 v15, v13, v14
	v_mul_f32_e64 v14, v12, v14
	v_mul_f32_e32 v12, v13, v125
	v_fmac_f32_e32 v79, v33, v12
	v_add_f32_e32 v12, -1.0, v4
	v_cvt_pk_bf16_f32 v61, v14, v15
	v_fma_f32 v13, v18, v12, 1.0
	s_nop 0
	v_mov_b32_e32 v14, v4
	v_mov_b32_e32 v15, v106
	v_mul_f32_e64 v12, v116, v14
	v_mul_f32_e64 v13, v13, v15
	v_mov_b32_e32 v106, v5
	v_mul_f32_e32 v4, v13, v126
	v_fmac_f32_e32 v79, v26, v4
	v_add_f32_e32 v4, -1.0, v5
	v_mul_f32_e64 v14, v12, v8
	v_mul_f32_e64 v15, v13, v8
	v_fma_f32 v13, v19, v4, 1.0
	v_rcp_f32_e32 v4, v9
	s_nop 0
	v_mul_f32_e64 v8, v117, v106
	v_mul_f32_e64 v9, v13, v107
	v_mov_b32_e32 v12, v6
	v_mul_f32_e64 v5, v9, v4
	v_mul_f32_e64 v4, v8, v4
	v_rcp_f32_e32 v8, v10
	v_cvt_pk_bf16_f32 v76, v4, v5
	v_mul_f32_e32 v4, v9, v127
	v_fmac_f32_e32 v79, v27, v4
	v_add_f32_e32 v4, -1.0, v6
	v_fma_f32 v5, v20, v4, 1.0
	s_nop 0
	v_mov_b32_e32 v13, v104
	v_mul_f32_e64 v4, v118, v12
	v_mul_f32_e64 v5, v5, v13
	v_rcp_f32_e32 v6, v11
	v_mul_f32_e64 v9, v5, v8
	v_mul_f32_e64 v8, v4, v8
	v_mul_f32_e32 v4, v5, v128
	v_fmac_f32_e32 v79, v28, v4
	v_add_f32_e32 v4, -1.0, v7
	v_fma_f32 v5, v21, v4, 1.0
	s_nop 0
	v_mov_b32_e32 v104, v7
	v_mul_f32_e64 v4, v119, v104
	v_mul_f32_e64 v5, v5, v105
	v_cvt_pk_bf16_f32 v58, v58, v59
	v_cvt_pk_bf16_f32 v14, v14, v15
	v_cvt_pk_bf16_f32 v8, v8, v9
	v_mul_f32_e64 v7, v5, v6
	v_mul_f32_e64 v6, v4, v6
	v_and_b32_e32 v59, 0xffff, v58
	v_and_b32_e32 v15, 0xffff, v14
	v_and_b32_e32 v9, 0xffff, v8
	v_cvt_pk_bf16_f32 v11, v6, v7
	v_mul_f32_e32 v4, v5, v129
	v_lshrrev_b32_e32 v60, 16, v58
	ds_write2_b32 v80, v58, v61 offset0:8 offset1:12
	v_lshrrev_b32_e32 v58, 16, v14
	v_lshrrev_b32_e32 v12, 16, v8
	v_fmac_f32_e32 v79, v29, v4
	v_lshl_or_b32 v4, v75, 16, v74
	v_lshl_or_b32 v5, v61, 16, v59
	v_lshl_or_b32 v6, v76, 16, v15
	v_lshl_or_b32 v7, v11, 16, v9
	s_mul_i32 s73, s76, 0x420000
	ds_write2_b32 v80, v14, v76 offset0:16 offset1:20
	ds_write2_b32 v80, v8, v11 offset0:24 offset1:28
	v_and_or_b32 v8, v75, s1, v78
	v_and_or_b32 v9, v61, s1, v60
	v_and_or_b32 v10, v76, s1, v58
	v_and_or_b32 v11, v11, s1, v12
	ds_write_b128 v195, v[4:7] offset:256
	ds_write_b128 v195, v[8:11] offset:384
	v_add_f32_dpp v4, v79, v79 quad_perm:[1,0,3,2] row_mask:0xf bank_mask:0xf bound_ctrl:1
	s_mul_hi_i32 s66, s76, 0x420000
	s_add_u32 s76, s43, s73
	v_add_f32_dpp v4, v4, v4 quad_perm:[2,3,0,1] row_mask:0xf bank_mask:0xf bound_ctrl:1
	s_addc_u32 s77, s95, s66
	s_nop 0
	v_mov_b32_dpp v5, v4 row_half_mirror row_mask:0xf bank_mask:0xf bound_ctrl:1
	s_and_saveexec_b64 s[80:81], s[8:9]
	s_cbranch_execz .LBB0_500
	v_lshlrev_b64 v[6:7], 6, v[102:103]
	v_lshl_add_u64 v[6:7], s[76:77], 0, v[6:7]
	s_lshl_b32 s66, s31, 2
	v_lshl_add_u64 v[6:7], v[6:7], 0, s[66:67]
	v_add_f32_e32 v4, v4, v5
	global_store_dword v[6:7], v4, off

; __device__ void phase_scan(const Params& p, char* lds) {
;     ...
;         const float inv = rsqrtf(fmaxf(ss, 1e-24f));
; #pragma unroll
;         for (int e = 0; e < 8; ++e) kk[e] *= inv;
;       };
;       auto stageB = [&](int c) {
;         char* buf = lds + (c & 1) * SC_BUF;
;         const f32x4 i0 = *(const f32x4*)(IC + pstep * 64 + j0), i1 = *(const f32x4*)(IC + pstep * 64 + j0 + 4);
;         const float ic[8] = {i0[0], i0[1], i0[2], i0[3], i1[0], i1[1], i1[2], i1[3]};
;         const float* Pt = (const float*)(buf + SC_P) + pstep * 64 + j0;
;         const f32x4 pt0 = *(const f32x4*)(Pt), pt1 = *(const f32x4*)(Pt + 4);
;         f32x4 pm0 = {1.f, 1.f, 1.f, 1.f}, pm1 = pm0;
;         if (pstep > 0) { pm0 = *(const f32x4*)(Pt - 64); pm1 = *(const f32x4*)(Pt - 60); }
;         const float pt[8] = {pt0[0], pt0[1], pt0[2], pt0[3], pt1[0], pt1[1], pt1[2], pt1[3]};
;         const float pm[8] = {pm0[0], pm0[1], pm0[2], pm0[3], pm1[0], pm1[1], pm1[2], pm1[3]};
;         const u32x4 an = {cvtpk(-kk[0] * pm[0], -kk[1] * pm[1]), cvtpk(-kk[2] * pm[2], -kk[3] * pm[3]), cvtpk(-kk[4] * pm[4], -kk[5] * pm[5]), cvtpk(-kk[6] * pm[6], -kk[7] * pm[7])};
;         const u32x4 rn = {cvtpk(rr[0] * pt[0], rr[1] * pt[1]), cvtpk(rr[2] * pt[2], rr[3] * pt[3]), cvtpk(rr[4] * pt[4], rr[5] * pt[5]), cvtpk(rr[6] * pt[6], rr[7] * pt[7])};
;         bf16_t* ARa = (bf16_t*)(buf + SC_ARA) + (pblk * 4 + psb) * 64; bf16_t* ARr = (bf16_t*)(buf + SC_ARR) + (pblk * 4 + psb) * 64;
;         { u32x2 lo = {an[0], an[1]}, hi2 = {an[2], an[3]}; *(u32x2*)(ARa + apos0) = lo; *(u32x2*)(ARa + apos1) = hi2; }
;         { u32x2 lo = {rn[0], rn[1]}, hi2 = {rn[2], rn[3]}; *(u32x2*)(ARr + apos0) = lo; *(u32x2*)(ARr + apos1) = hi2; }
;         *(u32x4*)(SCR + (pstep * 4 + 0) * 64 + j0) = an; *(u32x4*)(SCR + (pstep * 4 + 1) * 64 + j0) = rn;
;         float bs = 0.f;
;         unsigned bq[8], kq[8];
;         unsigned* BK = (unsigned*)(buf + SC_BK) + (pblk * 64 + j0) * 4 + psb;
; #pragma unroll
;         for (int e = 0; e < 8; ++e) {
;           const float kd = kr[e] * (1.f + (ic[e] - 1.f) * kac[e]);
;           const float ip = __builtin_amdgcn_rcpf(pt[e]);
;           const unsigned pr2 = cvtpk(kk[e] * ic[e] * ip, kd * ip);
;           BK[e * 4] = pr2;
;           bq[e] = pr2 & 0xffffu; kq[e] = pr2 >> 16;
;           bs += rr[e] * kd * rkc[e];
;         }
.LBB0_523:
	s_or_b64 exec, exec, s[78:79]
	v_add_f32_e32 v101, v101, v118
	v_max_f32_e32 v101, 0x179abe15, v101
	v_rsq_f32_e32 v118, v101
	v_lshlrev_b32_e32 v120, 16, v86
	v_and_b32_e32 v121, 0xffff0000, v86
	v_lshlrev_b32_e32 v122, 16, v87
	v_mul_f32_e64 v110, v110, v118
	v_mul_f32_e64 v111, v111, v118
	v_mul_f32_e64 v112, v112, v118
	v_mul_f32_e64 v113, v113, v118
	v_and_b32_e32 v123, 0xffff0000, v87
	v_lshlrev_b32_e32 v124, 16, v88
	v_and_b32_e32 v125, 0xffff0000, v88
	v_lshlrev_b32_e32 v126, 16, v89
	v_and_b32_e32 v127, 0xffff0000, v89
	v_mul_f32_e64 v114, v114, v118
	v_mul_f32_e64 v115, v115, v118
	v_mul_f32_e64 v116, v116, v118
	v_mul_f32_e64 v117, v117, v118
	s_waitcnt lgkmcnt(1)
	v_mul_f32_e64 v86, v94, -v110
	v_mul_f32_e64 v87, v95, -v111
	v_mul_f32_e64 v88, v96, -v112
	v_mul_f32_e64 v89, v97, -v113
	v_cvt_pk_bf16_f32 v86, v86, v87
	v_cvt_pk_bf16_f32 v87, v88, v89
	s_waitcnt lgkmcnt(0)
	v_mul_f32_e64 v88, v90, -v114
	v_mul_f32_e64 v89, v91, -v115
	v_mul_f32_e64 v90, v92, -v116
	v_mul_f32_e64 v91, v93, -v117
	v_cvt_pk_bf16_f32 v88, v88, v89
	v_cvt_pk_bf16_f32 v89, v90, v91
	v_mul_f32_e64 v90, v12, v120
	v_mul_f32_e64 v91, v13, v121
	v_mul_f32_e64 v92, v14, v122
	v_mul_f32_e64 v93, v15, v123
	v_cvt_pk_bf16_f32 v90, v90, v91
	v_cvt_pk_bf16_f32 v91, v92, v93
	v_mul_f32_e64 v92, v4, v124
	v_mul_f32_e64 v93, v5, v125
	v_mul_f32_e64 v94, v6, v126
	v_mul_f32_e64 v95, v7, v127
	v_cvt_pk_bf16_f32 v92, v92, v93
	v_cvt_pk_bf16_f32 v93, v94, v95
	v_add_u32_e32 v94, 0xa000, v194
	ds_write2_b64 v94, v[86:87], v[88:89] offset0:128 offset1:130
	v_add_u32_e32 v94, 0xb000, v194
	ds_write2_b64 v94, v[90:91], v[92:93] offset0:128 offset1:130
	ds_write_b128 v195, v[86:89]
	ds_write_b128 v195, v[90:93] offset:128
	v_add_f32_e32 v86, -1.0, v8
	v_fma_f32 v87, v22, v86, 1.0
	v_rcp_f32_e32 v12, v12
	s_nop 0
	v_mov_b32_e32 v88, v8
	v_mov_b32_e32 v89, v108
	v_mul_f32_e64 v86, v110, v88
	v_mul_f32_e64 v87, v87, v89
	v_mov_b32_e32 v108, v9
	v_mul_f32_e32 v8, v87, v120
	v_fma_f32 v91, v30, v8, 0
	v_add_f32_e32 v8, -1.0, v9
	v_mul_f32_e64 v88, v86, v12
	v_mul_f32_e64 v89, v87, v12
	v_fma_f32 v87, v23, v8, 1.0
	v_rcp_f32_e32 v8, v13
	s_nop 0
	v_mul_f32_e64 v12, v111, v108
	v_mul_f32_e64 v13, v87, v109
	v_mov_b32_e32 v86, v10
	v_mul_f32_e64 v9, v13, v8
	v_mul_f32_e64 v8, v12, v8
	v_rcp_f32_e32 v12, v14
	v_cvt_pk_bf16_f32 v92, v8, v9
	v_mul_f32_e32 v8, v13, v121
	v_fmac_f32_e32 v91, v31, v8
	v_add_f32_e32 v8, -1.0, v10
	v_fma_f32 v9, v24, v8, 1.0
	s_nop 0
	v_mov_b32_e32 v87, v106
	v_mul_f32_e64 v8, v112, v86
	v_mul_f32_e64 v9, v9, v87
	v_rcp_f32_e32 v10, v15
	v_mul_f32_e64 v13, v9, v12
	v_mul_f32_e64 v12, v8, v12
	v_mul_f32_e32 v8, v9, v122
	v_fmac_f32_e32 v91, v32, v8
	v_add_f32_e32 v8, -1.0, v11
	v_fma_f32 v9, v25, v8, 1.0
	s_nop 0
	v_mov_b32_e32 v106, v11
	v_mul_f32_e64 v8, v113, v106
	v_mul_f32_e64 v9, v9, v107
	v_rcp_f32_e32 v4, v4
	v_mul_f32_e64 v11, v9, v10
	v_mul_f32_e64 v10, v8, v10
	v_mul_f32_e32 v8, v9, v123
	v_fmac_f32_e32 v91, v33, v8
	v_add_f32_e32 v8, -1.0, v0
	v_cvt_pk_bf16_f32 v15, v10, v11
	v_fma_f32 v9, v18, v8, 1.0
	s_nop 0
	v_mov_b32_e32 v10, v0
	v_mov_b32_e32 v11, v104
	v_mul_f32_e64 v8, v114, v10
	v_mul_f32_e64 v9, v9, v11
	v_mov_b32_e32 v104, v1
	v_mul_f32_e32 v0, v9, v124
	v_fmac_f32_e32 v91, v26, v0
	v_add_f32_e32 v0, -1.0, v1
	v_mul_f32_e64 v10, v8, v4
	v_mul_f32_e64 v11, v9, v4
	v_fma_f32 v9, v19, v0, 1.0
	v_rcp_f32_e32 v0, v5
	s_nop 0
	v_mul_f32_e64 v4, v115, v104
	v_mul_f32_e64 v5, v9, v105
	v_mov_b32_e32 v8, v2
	v_mul_f32_e64 v1, v5, v0
	v_mul_f32_e64 v0, v4, v0
	v_rcp_f32_e32 v4, v6
	v_cvt_pk_bf16_f32 v86, v0, v1
	v_mul_f32_e32 v0, v5, v125
	v_fmac_f32_e32 v91, v27, v0
	v_add_f32_e32 v0, -1.0, v2
	v_fma_f32 v1, v20, v0, 1.0
	s_nop 0
	v_mov_b32_e32 v9, v102
	v_mul_f32_e64 v0, v116, v8
	v_mul_f32_e64 v1, v1, v9
	v_rcp_f32_e32 v2, v7
	v_mul_f32_e64 v5, v1, v4
	v_mul_f32_e64 v4, v0, v4
	v_mul_f32_e32 v0, v1, v126
	v_fmac_f32_e32 v91, v28, v0
	v_add_f32_e32 v0, -1.0, v3
	v_fma_f32 v1, v21, v0, 1.0
	s_nop 0
	v_mov_b32_e32 v102, v3
	v_mul_f32_e64 v0, v117, v102
	v_mul_f32_e64 v1, v1, v103
	v_cvt_pk_bf16_f32 v88, v88, v89
	v_cvt_pk_bf16_f32 v12, v12, v13
	v_cvt_pk_bf16_f32 v10, v10, v11
	v_cvt_pk_bf16_f32 v4, v4, v5
	v_mul_f32_e64 v3, v1, v2
	v_mul_f32_e64 v2, v0, v2
	v_and_b32_e32 v89, 0xffff, v88
	v_add_u32_e32 v93, 0xc400, v198
	v_and_b32_e32 v13, 0xffff, v12
	v_and_b32_e32 v11, 0xffff, v10
	v_and_b32_e32 v5, 0xffff, v4
	v_cvt_pk_bf16_f32 v7, v2, v3
	v_mul_f32_e32 v0, v1, v127
	v_lshrrev_b32_e32 v90, 16, v88
	v_lshrrev_b32_e32 v14, 16, v12
	ds_write2_b32 v93, v12, v15 offset0:8 offset1:12
	v_lshrrev_b32_e32 v12, 16, v10
	v_lshrrev_b32_e32 v8, 16, v4
	v_fmac_f32_e32 v91, v29, v0
	v_lshl_or_b32 v0, v92, 16, v89
	v_lshl_or_b32 v1, v15, 16, v13
	v_lshl_or_b32 v2, v86, 16, v11
	v_lshl_or_b32 v3, v7, 16, v5
	s_lshl_b32 s31, s31, 2
	ds_write2_b32 v93, v88, v92 offset1:4
	ds_write2_b32 v93, v10, v86 offset0:16 offset1:20
	ds_write2_b32 v93, v4, v7 offset0:24 offset1:28
	v_and_or_b32 v4, v92, s1, v90
	v_and_or_b32 v5, v15, s1, v14
	v_and_or_b32 v6, v86, s1, v12
	v_and_or_b32 v7, v7, s1, v8
	ds_write_b128 v195, v[0:3] offset:256
	ds_write_b128 v195, v[4:7] offset:384
	v_add_f32_dpp v0, v91, v91 quad_perm:[1,0,3,2] row_mask:0xf bank_mask:0xf bound_ctrl:1
	s_add_u32 s76, s76, s31
	s_addc_u32 s77, s77, 0
	v_add_f32_dpp v0, v0, v0 quad_perm:[2,3,0,1] row_mask:0xf bank_mask:0xf bound_ctrl:1
	s_nop 1
	v_mov_b32_dpp v1, v0 row_half_mirror row_mask:0xf bank_mask:0xf bound_ctrl:1
	s_and_saveexec_b64 s[78:79], s[8:9]
	s_cbranch_execz .LBB0_525
	v_add_f32_e32 v2, v0, v1
	v_lshlrev_b64 v[0:1], 6, v[16:17]
	v_lshl_add_u64 v[0:1], s[76:77], 0, v[0:1]
	global_store_dword v[0:1], v2, off

; __device__ void phase_scan(const Params& p, char* lds) {
;     ...
;         const float inv = rsqrtf(fmaxf(ss, 1e-24f));
; #pragma unroll
;         for (int e = 0; e < 8; ++e) kk[e] *= inv;
;       };
;       auto stageB = [&](int c) {
;         char* buf = lds + (c & 1) * SC_BUF;
;         const f32x4 i0 = *(const f32x4*)(IC + pstep * 64 + j0), i1 = *(const f32x4*)(IC + pstep * 64 + j0 + 4);
;         const float ic[8] = {i0[0], i0[1], i0[2], i0[3], i1[0], i1[1], i1[2], i1[3]};
;         const float* Pt = (const float*)(buf + SC_P) + pstep * 64 + j0;
;         const f32x4 pt0 = *(const f32x4*)(Pt), pt1 = *(const f32x4*)(Pt + 4);
;         f32x4 pm0 = {1.f, 1.f, 1.f, 1.f}, pm1 = pm0;
;         if (pstep > 0) { pm0 = *(const f32x4*)(Pt - 64); pm1 = *(const f32x4*)(Pt - 60); }
;         const float pt[8] = {pt0[0], pt0[1], pt0[2], pt0[3], pt1[0], pt1[1], pt1[2], pt1[3]};
;         const float pm[8] = {pm0[0], pm0[1], pm0[2], pm0[3], pm1[0], pm1[1], pm1[2], pm1[3]};
;         const u32x4 an = {cvtpk(-kk[0] * pm[0], -kk[1] * pm[1]), cvtpk(-kk[2] * pm[2], -kk[3] * pm[3]), cvtpk(-kk[4] * pm[4], -kk[5] * pm[5]), cvtpk(-kk[6] * pm[6], -kk[7] * pm[7])};
;         const u32x4 rn = {cvtpk(rr[0] * pt[0], rr[1] * pt[1]), cvtpk(rr[2] * pt[2], rr[3] * pt[3]), cvtpk(rr[4] * pt[4], rr[5] * pt[5]), cvtpk(rr[6] * pt[6], rr[7] * pt[7])};
;         bf16_t* ARa = (bf16_t*)(buf + SC_ARA) + (pblk * 4 + psb) * 64; bf16_t* ARr = (bf16_t*)(buf + SC_ARR) + (pblk * 4 + psb) * 64;
;         { u32x2 lo = {an[0], an[1]}, hi2 = {an[2], an[3]}; *(u32x2*)(ARa + apos0) = lo; *(u32x2*)(ARa + apos1) = hi2; }
;         { u32x2 lo = {rn[0], rn[1]}, hi2 = {rn[2], rn[3]}; *(u32x2*)(ARr + apos0) = lo; *(u32x2*)(ARr + apos1) = hi2; }
;         *(u32x4*)(SCR + (pstep * 4 + 0) * 64 + j0) = an; *(u32x4*)(SCR + (pstep * 4 + 1) * 64 + j0) = rn;
;         float bs = 0.f;
;         unsigned bq[8], kq[8];
;         unsigned* BK = (unsigned*)(buf + SC_BK) + (pblk * 64 + j0) * 4 + psb;
; #pragma unroll
;         for (int e = 0; e < 8; ++e) {
;           const float kd = kr[e] * (1.f + (ic[e] - 1.f) * kac[e]);
;           const float ip = __builtin_amdgcn_rcpf(pt[e]);
;           const unsigned pr2 = cvtpk(kk[e] * ic[e] * ip, kd * ip);
;           BK[e * 4] = pr2;
;           bq[e] = pr2 & 0xffffu; kq[e] = pr2 >> 16;
;           bs += rr[e] * kd * rkc[e];
;         }
.LBB0_552:
	s_or_b64 exec, exec, s[80:81]
	v_add_f32_e32 v123, v123, v124
	v_max_f32_e32 v123, 0x179abe15, v123
	v_rsq_f32_e32 v124, v123
	v_lshlrev_b32_e32 v126, 16, v75
	v_and_b32_e32 v127, 0xffff0000, v75
	v_lshlrev_b32_e32 v128, 16, v76
	v_mul_f32_e64 v112, v112, v124
	v_mul_f32_e64 v113, v113, v124
	v_mul_f32_e64 v114, v114, v124
	v_mul_f32_e64 v115, v115, v124
	v_mul_f32_e64 v116, v116, v124
	v_mul_f32_e64 v117, v117, v124
	v_mul_f32_e64 v118, v118, v124
	v_mul_f32_e64 v119, v119, v124
	v_lshlrev_b32_e32 v124, 16, v74
	v_and_b32_e32 v125, 0xffff0000, v74
	v_and_b32_e32 v129, 0xffff0000, v76
	v_lshlrev_b32_e32 v130, 16, v77
	v_and_b32_e32 v131, 0xffff0000, v77
	s_waitcnt lgkmcnt(1)
	v_mul_f32_e64 v74, v94, -v112
	v_mul_f32_e64 v75, v95, -v113
	v_mul_f32_e64 v76, v96, -v114
	v_mul_f32_e64 v77, v97, -v115
	v_cvt_pk_bf16_f32 v74, v74, v75
	v_cvt_pk_bf16_f32 v75, v76, v77
	s_waitcnt lgkmcnt(0)
	v_mul_f32_e64 v76, v90, -v116
	v_mul_f32_e64 v77, v91, -v117
	v_mul_f32_e64 v90, v92, -v118
	v_mul_f32_e64 v91, v93, -v119
	v_cvt_pk_bf16_f32 v76, v76, v77
	v_cvt_pk_bf16_f32 v77, v90, v91
	v_mul_f32_e64 v90, v124, v86
	v_mul_f32_e64 v91, v125, v87
	v_mul_f32_e64 v92, v126, v88
	v_mul_f32_e64 v93, v127, v89
	v_cvt_pk_bf16_f32 v90, v90, v91
	v_cvt_pk_bf16_f32 v91, v92, v93
	v_mul_f32_e64 v92, v128, v78
	v_mul_f32_e64 v93, v129, v79
	v_mul_f32_e64 v94, v130, v80
	v_mul_f32_e64 v95, v131, v81
	v_cvt_pk_bf16_f32 v92, v92, v93
	v_cvt_pk_bf16_f32 v93, v94, v95
	v_add3_u32 v94, s90, v192, v193
	v_add_u32_e32 v95, 0x2000, v94
	v_add_u32_e32 v94, 0x3000, v94
	ds_write2_b64 v95, v[74:75], v[76:77] offset1:2
	ds_write2_b64 v94, v[90:91], v[92:93] offset1:2
	ds_write_b128 v195, v[74:77]
	ds_write_b128 v195, v[90:93] offset:128
	v_rcp_f32_e32 v76, v86
	v_add_f32_e32 v74, -1.0, v82
	v_fma_f32 v75, v22, v74, 1.0
	s_nop 0
	v_mov_b32_e32 v91, v110
	s_nop 0
	v_mul_f32_e64 v74, v112, v82
	v_mul_f32_e64 v75, v91, v75
	v_mov_b32_e32 v110, v113
	v_mul_f32_e64 v77, v75, v76
	v_mul_f32_e64 v76, v74, v76
	v_mul_f32_e32 v74, v124, v75
	v_cvt_pk_bf16_f32 v82, v76, v77
	v_rcp_f32_e32 v76, v87
	v_fma_f32 v91, v30, v74, 0
	v_add_f32_e32 v74, -1.0, v83
	v_fma_f32 v75, v23, v74, 1.0
	s_nop 0
	v_mul_f32_e64 v74, v110, v83
	v_mul_f32_e64 v75, v111, v75
	v_add3_u32 v92, s90, v196, v197
	v_mul_f32_e64 v77, v75, v76
	v_mul_f32_e64 v76, v74, v76
	v_mul_f32_e32 v74, v125, v75
	v_cvt_pk_bf16_f32 v87, v76, v77
	v_rcp_f32_e32 v76, v88
	v_add_u32_e32 v92, 0x4000, v92
	v_fmac_f32_e32 v91, v31, v74
	v_add_f32_e32 v74, -1.0, v84
	v_and_b32_e32 v86, 0xffff, v82
	v_lshrrev_b32_e32 v90, 16, v82
	ds_write2_b32 v92, v82, v87 offset1:4
	v_fma_f32 v75, v24, v74, 1.0
	s_nop 0
	v_mov_b32_e32 v83, v108
	s_nop 0
	v_mul_f32_e64 v74, v114, v84
	v_mul_f32_e64 v75, v83, v75
	v_mov_b32_e32 v108, v115
	v_mul_f32_e64 v77, v75, v76
	v_mul_f32_e64 v76, v74, v76
	v_mul_f32_e32 v74, v126, v75
	v_cvt_pk_bf16_f32 v82, v76, v77
	v_rcp_f32_e32 v76, v89
	v_fmac_f32_e32 v91, v32, v74
	v_add_f32_e32 v74, -1.0, v85
	v_fma_f32 v75, v25, v74, 1.0
	s_nop 0
	v_mul_f32_e64 v74, v108, v85
	v_mul_f32_e64 v75, v109, v75
	v_and_b32_e32 v84, 0xffff, v82
	v_mul_f32_e64 v77, v75, v76
	v_mul_f32_e64 v76, v74, v76
	v_mul_f32_e32 v74, v127, v75
	v_cvt_pk_bf16_f32 v85, v76, v77
	v_fmac_f32_e32 v91, v33, v74
	v_add_f32_e32 v74, -1.0, v12
	v_lshrrev_b32_e32 v88, 16, v82
	ds_write2_b32 v92, v82, v85 offset0:8 offset1:12
	v_fma_f32 v75, v18, v74, 1.0
	v_rcp_f32_e32 v76, v78
	s_nop 0
	v_mov_b32_e32 v83, v106
	s_nop 0
	v_mul_f32_e64 v74, v116, v12
	v_mul_f32_e64 v75, v83, v75
	v_mov_b32_e32 v106, v117
	v_mul_f32_e32 v12, v128, v75
	v_fmac_f32_e32 v91, v26, v12
	v_add_f32_e32 v12, -1.0, v13
	v_mul_f32_e64 v77, v75, v76
	v_mul_f32_e64 v76, v74, v76
	v_fma_f32 v75, v19, v12, 1.0
	v_rcp_f32_e32 v12, v79
	s_nop 0
	v_mul_f32_e64 v74, v106, v13
	v_mul_f32_e64 v75, v107, v75
	v_cvt_pk_bf16_f32 v76, v76, v77
	v_mul_f32_e64 v13, v75, v12
	v_mul_f32_e64 v12, v74, v12
	v_rcp_f32_e32 v74, v80
	v_cvt_pk_bf16_f32 v79, v12, v13
	v_mul_f32_e32 v12, v129, v75
	v_fmac_f32_e32 v91, v27, v12
	v_add_f32_e32 v12, -1.0, v14
	v_and_b32_e32 v78, 0xffff, v76
	v_lshrrev_b32_e32 v82, 16, v76
	ds_write2_b32 v92, v76, v79 offset0:16 offset1:20
	v_fma_f32 v13, v20, v12, 1.0
	s_nop 0
	v_mov_b32_e32 v77, v104
	s_nop 0
	v_mul_f32_e64 v12, v118, v14
	v_mul_f32_e64 v13, v77, v13
	v_rcp_f32_e32 v14, v81
	v_mul_f32_e64 v75, v13, v74
	v_mul_f32_e64 v74, v12, v74
	v_mul_f32_e32 v12, v130, v13
	v_fmac_f32_e32 v91, v28, v12
	v_add_f32_e32 v12, -1.0, v15
	v_fma_f32 v13, v21, v12, 1.0
	v_mov_b32_e32 v104, v119
	s_nop 0
	v_mul_f32_e64 v12, v104, v15
	v_mul_f32_e64 v13, v105, v13
	v_cvt_pk_bf16_f32 v74, v74, v75
	v_mul_f32_e64 v15, v13, v14
	v_mul_f32_e64 v14, v12, v14
	v_and_b32_e32 v75, 0xffff, v74
	v_cvt_pk_bf16_f32 v80, v14, v15
	v_mul_f32_e32 v12, v131, v13
	v_lshrrev_b32_e32 v77, 16, v74
	v_fmac_f32_e32 v91, v29, v12
	v_lshl_or_b32 v12, v87, 16, v86
	v_lshl_or_b32 v13, v85, 16, v84
	v_lshl_or_b32 v14, v79, 16, v78
	v_lshl_or_b32 v15, v80, 16, v75
	ds_write2_b32 v92, v74, v80 offset0:24 offset1:28
	v_and_or_b32 v74, v87, s1, v90
	v_and_or_b32 v75, v85, s1, v88
	v_and_or_b32 v76, v79, s1, v82
	v_and_or_b32 v77, v80, s1, v77
	ds_write_b128 v195, v[12:15] offset:256
	ds_write_b128 v195, v[74:77] offset:384
	v_add_f32_dpp v12, v91, v91 quad_perm:[1,0,3,2] row_mask:0xf bank_mask:0xf bound_ctrl:1
	s_nop 1
	v_add_f32_dpp v12, v12, v12 quad_perm:[2,3,0,1] row_mask:0xf bank_mask:0xf bound_ctrl:1
	s_nop 1
	v_mov_b32_dpp v13, v12 row_half_mirror row_mask:0xf bank_mask:0xf bound_ctrl:1
	s_and_saveexec_b64 s[80:81], s[8:9]
	s_cbranch_execz .LBB0_554
	v_add_f32_e32 v14, v12, v13
	v_add_u32_e32 v12, 64, v122
	v_cmp_gt_i32_e32 vcc, s92, v12
	v_add_u32_e32 v13, 0xffffff40, v122
	s_movk_i32 s88, 0xffc0
	v_cndmask_b32_e32 v15, v220, v221, vcc
	v_cndmask_b32_e32 v12, v13, v12, vcc
	v_mov_b32_e32 v13, s34
	v_mov_b32_e32 v74, s35
	v_add3_u32 v15, v15, v120, s88
	v_cndmask_b32_e32 v13, v13, v74, vcc
	v_cndmask_b32_e64 v12, v15, v12, s[22:23]
	v_add_u32_e32 v12, v12, v13
	v_ashrrev_i32_e32 v13, 31, v12
	v_lshlrev_b64 v[12:13], 6, v[12:13]
	v_lshl_add_u64 v[12:13], s[76:77], 0, v[12:13]
	global_store_dword v[12:13], v14, off

; __device__ __forceinline__ void st_bf16x4(bf16_t* p, float a, float b, float c, float d) { u32x2 w = {cvtpk(a, b), cvtpk(c, d)}; *(u32x2*)p = w; }
; __device__ void phase_norm(const float* xsrc, const float* csrc, const float* ng, const float* mod, bf16_t* H) {
;     ...
;   for (int n = gw; n < NTOK; n += nw) {
;     if (n + nw < NTOK) { const float* src = row_src(xsrc, csrc, n + nw, bib);
; #pragma unroll
;       for (int i = 0; i < 4; ++i) vb[i] = *(const f32x4*)(src + i * 256 + lane * 4); }
;     float ss = 0.f;
; #pragma unroll
;     for (int i = 0; i < 4; ++i) ss += va[i][0] * va[i][0] + va[i][1] * va[i][1] + va[i][2] * va[i][2] + va[i][3] * va[i][3];
;     ss = wave_sum(ss);
;     const float rstd = rsqrtf(ss * (1.f / 1024.f) + 1e-6f);
;     const float* m = mod + bia * 3072;
; #pragma unroll
;     for (int i = 0; i < 4; ++i) {
;       const int c = i * 256 + lane * 4;
;       const f32x4 sh = *(const f32x4*)(m + c), sc = *(const f32x4*)(m + 1024 + c);
;       float o[4];
; #pragma unroll
;       for (int e = 0; e < 4; ++e) o[e] = va[i][e] * rstd * g4[i][e] * (1.f + sc[e]) + sh[e];
;       st_bf16x4(H + (size_t)n * 1024 + c, o[0], o[1], o[2], o[3]);
;     }
; #pragma unroll
;     for (int i = 0; i < 4; ++i) va[i] = vb[i];
;     bia = bib;
;   }
.LBB0_683:
	s_or_b64 exec, exec, s[18:19]
	s_waitcnt vmcnt(11)
	v_mul_lo_u32 v66, v51, s22
	v_ashrrev_i32_e32 v67, 31, v66
	s_waitcnt vmcnt(10)
	v_lshl_add_u64 v[70:71], v[66:67], 2, s[10:11]
	v_lshl_add_u64 v[74:75], v[70:71], 0, s[16:17]
	v_lshl_add_u64 v[66:67], v[74:75], 0, v[166:167]
	global_load_dwordx4 v[66:69], v[66:67], off
	v_lshl_add_u64 v[76:77], v[70:71], 0, v[166:167]
	global_load_dwordx4 v[70:73], v[76:77], off
	s_waitcnt vmcnt(3)
	s_nop 0
	s_waitcnt vmcnt(2)
	s_nop 0
	s_nop 0
	s_nop 0
	s_nop 0
	s_nop 0
	v_mul_f32_e64 v80, v25, v25
	v_mul_f32_e64 v81, v29, v29
	v_mov_b32_e32 v82, v26
	v_mov_b32_e32 v83, v30
	v_mov_b32_e32 v86, v16
	v_mov_b32_e32 v87, v20
	v_mul_f32_e64 v88, v17, v17
	v_mul_f32_e64 v89, v21, v21
	v_fma_f32 v78, v24, v24, v80
	v_fma_f32 v79, v28, v28, v81
	v_mov_b32_e32 v84, v27
	v_mov_b32_e32 v85, v31
	v_mov_b32_e32 v90, v18
	v_mov_b32_e32 v91, v22
	v_fma_f32 v80, v86, v86, v88
	v_fma_f32 v81, v87, v87, v89
	v_fma_f32 v78, v82, v82, v78
	v_fma_f32 v79, v83, v83, v79
	v_mov_b32_e32 v92, v19
	v_mov_b32_e32 v93, v23
	v_fma_f32 v80, v90, v90, v80
	v_fma_f32 v81, v91, v91, v81
	v_fma_f32 v78, v84, v84, v78
	v_fma_f32 v79, v85, v85, v79
	v_fma_f32 v80, v92, v92, v80
	v_fma_f32 v81, v93, v93, v81
	v_add_f32_e32 v51, v78, v79
	v_add_f32_e32 v51, v81, v51
	v_add_f32_e32 v51, v80, v51
	ds_bpermute_b32 v53, v56, v51
	s_and_b64 s[4:5], exec, vcc
	v_mov_b32_e32 v55, v167
	s_or_b64 s[14:15], s[4:5], s[14:15]
	s_waitcnt lgkmcnt(0)
	v_add_f32_e32 v51, v51, v53
	ds_bpermute_b32 v53, v57, v51
	s_waitcnt lgkmcnt(0)
	v_add_f32_e32 v51, v51, v53
	ds_bpermute_b32 v53, v58, v51
	s_waitcnt lgkmcnt(0)
	v_add_f32_e32 v51, v51, v53
	ds_bpermute_b32 v53, v59, v51
	s_waitcnt lgkmcnt(0)
	v_add_f32_e32 v51, v51, v53
	ds_bpermute_b32 v53, v60, v51
	s_waitcnt lgkmcnt(0)
	v_add_f32_e32 v51, v51, v53
	ds_bpermute_b32 v53, v61, v51
	s_waitcnt lgkmcnt(0)
	v_add_f32_e32 v51, v51, v53
	v_fmamk_f32 v51, v51, 0x3a800000, v62
	v_mul_f32_e32 v53, 0x4b800000, v51
	v_cmp_gt_f32_e32 vcc, s21, v51
	s_waitcnt vmcnt(1)
	v_add_f32_e64 v66, v66, 1.0
	v_add_f32_e64 v67, v67, 1.0
	v_cndmask_b32_e32 v51, v51, v53, vcc
	v_rsq_f32_e32 v53, v51
	v_mov_b32_e32 v51, v167
	v_lshl_add_u64 v[78:79], v[74:75], 0, v[50:51]
	v_add_f32_e64 v68, v68, 1.0
	v_add_f32_e64 v69, v69, 1.0
	v_mul_f32_e32 v51, 0x45800000, v53
	v_cndmask_b32_e32 v80, v53, v51, vcc
	v_mul_f32_e64 v28, v28, v80
	v_mul_f32_e64 v29, v29, v80
	v_mul_f32_e64 v30, v30, v80
	v_mul_f32_e64 v31, v31, v80
	v_mul_f32_e64 v28, v8, v28
	v_mul_f32_e64 v29, v9, v29
	v_mul_f32_e64 v30, v10, v30
	v_mul_f32_e64 v31, v11, v31
	s_waitcnt vmcnt(0)
	v_fma_f32 v28, v66, v28, v70
	v_fma_f32 v29, v67, v29, v71
	v_fma_f32 v30, v68, v30, v72
	v_fma_f32 v31, v69, v31, v73
	v_cvt_pk_bf16_f32 v28, v28, v29
	v_cvt_pk_bf16_f32 v29, v30, v31
	global_store_dwordx2 v[48:49], v[28:29], off offset:-1024
	global_load_dwordx4 v[28:31], v[78:79], off
	s_nop 0
	global_load_dwordx4 v[66:69], v[76:77], off offset:1024
	v_mul_f32_e64 v24, v24, v80
	v_mul_f32_e64 v25, v25, v80
	v_mul_f32_e64 v26, v26, v80
	v_mul_f32_e64 v27, v27, v80
	v_mul_f32_e64 v24, v0, v24
	v_mul_f32_e64 v25, v1, v25
	v_mul_f32_e64 v26, v2, v26
	v_mul_f32_e64 v27, v3, v27
	v_mov_b32_e32 v53, v167
	v_lshl_add_u64 v[70:71], v[74:75], 0, v[52:53]
	v_mul_f32_e64 v20, v20, v80
	v_mul_f32_e64 v21, v21, v80
	v_mul_f32_e64 v22, v22, v80
	v_mul_f32_e64 v23, v23, v80
	v_mul_f32_e64 v20, v4, v20
	v_mul_f32_e64 v21, v5, v21
	v_mul_f32_e64 v22, v6, v22
	v_mul_f32_e64 v23, v7, v23
	v_lshl_add_u64 v[74:75], v[74:75], 0, v[54:55]
	v_mov_b32_e32 v53, v63
	v_mov_b32_e32 v51, v64
	s_waitcnt vmcnt(1)
	v_add_f32_e64 v28, v28, 1.0
	v_add_f32_e64 v29, v29, 1.0
	v_add_f32_e64 v30, v30, 1.0
	v_add_f32_e64 v31, v31, 1.0
	s_waitcnt vmcnt(0)
	v_fma_f32 v24, v28, v24, v66
	v_fma_f32 v25, v29, v25, v67
	v_fma_f32 v26, v30, v26, v68
	v_fma_f32 v27, v31, v27, v69
	v_cvt_pk_bf16_f32 v24, v24, v25
	v_cvt_pk_bf16_f32 v25, v26, v27
	global_store_dwordx2 v[48:49], v[24:25], off offset:-512
	global_load_dwordx4 v[24:27], v[70:71], off
	s_nop 0
	global_load_dwordx4 v[28:31], v[76:77], off offset:2048
	s_waitcnt vmcnt(1)
	v_add_f32_e64 v24, v24, 1.0
	v_add_f32_e64 v25, v25, 1.0
	v_add_f32_e64 v26, v26, 1.0
	v_add_f32_e64 v27, v27, 1.0
	s_waitcnt vmcnt(0)
	v_fma_f32 v20, v24, v20, v28
	v_fma_f32 v21, v25, v21, v29
	v_fma_f32 v22, v26, v22, v30
	v_fma_f32 v23, v27, v23, v31
	v_cvt_pk_bf16_f32 v20, v20, v21
	v_cvt_pk_bf16_f32 v21, v22, v23
	global_store_dwordx2 v[48:49], v[20:21], off
	global_load_dwordx4 v[66:69], v[74:75], off
	global_load_dwordx4 v[70:73], v[76:77], off offset:3072
	v_mul_f32_e64 v74, v16, v80
	v_mul_f32_e64 v75, v17, v80
	v_mul_f32_e64 v76, v18, v80
	v_mul_f32_e64 v77, v19, v80
	v_mul_f32_e64 v74, v12, v74
	v_mul_f32_e64 v75, v13, v75
	v_mul_f32_e64 v76, v14, v76
	v_mul_f32_e64 v77, v15, v77
	v_mov_b64_e32 v[16:17], v[44:45]
	v_mov_b64_e32 v[20:21], v[40:41]
	v_mov_b64_e32 v[24:25], v[36:37]
	v_mov_b64_e32 v[28:29], v[32:33]
	v_mov_b64_e32 v[18:19], v[46:47]
	v_mov_b64_e32 v[22:23], v[42:43]
	v_mov_b64_e32 v[26:27], v[38:39]
	v_mov_b64_e32 v[30:31], v[34:35]
	s_waitcnt vmcnt(1)
	v_add_f32_e64 v66, v66, 1.0
	v_add_f32_e64 v67, v67, 1.0
	v_add_f32_e64 v68, v68, 1.0
	v_add_f32_e64 v69, v69, 1.0
	s_waitcnt vmcnt(0)
	v_fma_f32 v66, v74, v66, v70
	v_fma_f32 v67, v75, v67, v71
	v_fma_f32 v68, v76, v68, v72
	v_fma_f32 v69, v77, v69, v73
	v_cvt_pk_bf16_f32 v66, v66, v67
	v_cvt_pk_bf16_f32 v67, v68, v69
	global_store_dwordx2 v[48:49], v[66:67], off offset:512
	v_lshl_add_u64 v[48:49], v[48:49], 0, s[12:13]
	s_andn2_b64 exec, exec, s[14:15]
	s_cbranch_execz .LBB0_689

; __device__ void phase_final(float* out, const float* fg) {
;     ...
;   for (int n = gw; n < NB * T; n += nw) {
;     if (n + nw < NB * T) {
; #pragma unroll
;       for (int i = 0; i < 4; ++i) vb[i] = *(const f32x4*)(out + (size_t)(n + nw) * D + i * 256 + lane * 4); }
;     float ss = 0.f;
; #pragma unroll
;     for (int i = 0; i < 4; ++i) ss += va[i][0] * va[i][0] + va[i][1] * va[i][1] + va[i][2] * va[i][2] + va[i][3] * va[i][3];
;     ss = wave_sum(ss);
;     const float rstd = rsqrtf(ss * (1.f / 1024.f) + 1e-6f);
; #pragma unroll
;     for (int i = 0; i < 4; ++i) {
;       f32x4 o;
; #pragma unroll
;       for (int e = 0; e < 4; ++e) o[e] = va[i][e] * rstd * g4[i][e];
;       *(f32x4*)(out + (size_t)n * D + i * 256 + lane * 4) = o;
;     }
; #pragma unroll
;     for (int i = 0; i < 4; ++i) va[i] = vb[i];
;   }
.LBB0_1051:
	s_or_b64 exec, exec, s[6:7]
	s_waitcnt vmcnt(2)
	s_nop 0
	s_nop 0
	s_nop 0
	s_nop 0
	v_mul_f32_e64 v62, v25, v25
	v_mul_f32_e64 v63, v29, v29
	s_waitcnt vmcnt(0)
	s_nop 0
	v_fma_f32 v60, v24, v24, v62
	v_fma_f32 v61, v28, v28, v63
	s_nop 0
	s_nop 0
	v_fma_f32 v60, v26, v26, v60
	v_fma_f32 v61, v30, v30, v61
	s_nop 0
	s_nop 0
	s_nop 0
	v_fma_f32 v60, v27, v27, v60
	v_fma_f32 v61, v31, v31, v61
	s_nop 0
	s_nop 0
	v_mul_f32_e64 v64, v17, v17
	v_mul_f32_e64 v65, v21, v21
	v_add_f32_e32 v59, v60, v61
	v_fma_f32 v62, v16, v16, v64
	v_fma_f32 v63, v20, v20, v65
	s_nop 0
	s_nop 0
	v_fma_f32 v62, v18, v18, v62
	v_fma_f32 v63, v22, v22, v63
	v_mov_b32_e32 v64, v19
	v_mov_b32_e32 v65, v23
	v_fma_f32 v62, v64, v64, v62
	v_fma_f32 v63, v65, v65, v63
	s_and_b64 s[6:7], exec, vcc
	v_add_f32_e32 v59, v63, v59
	v_add_f32_e32 v59, v62, v59
	ds_bpermute_b32 v60, v52, v59
	s_or_b64 s[4:5], s[6:7], s[4:5]
	v_lshl_add_u64 v[50:51], v[50:51], 0, s[2:3]
	s_waitcnt lgkmcnt(0)
	v_add_f32_e32 v59, v59, v60
	ds_bpermute_b32 v60, v53, v59
	s_waitcnt lgkmcnt(0)
	v_add_f32_e32 v59, v59, v60
	ds_bpermute_b32 v60, v54, v59
	s_waitcnt lgkmcnt(0)
	v_add_f32_e32 v59, v59, v60
	ds_bpermute_b32 v60, v55, v59
	s_waitcnt lgkmcnt(0)
	v_add_f32_e32 v59, v59, v60
	ds_bpermute_b32 v60, v56, v59
	s_waitcnt lgkmcnt(0)
	v_add_f32_e32 v59, v59, v60
	ds_bpermute_b32 v60, v57, v59
	s_waitcnt lgkmcnt(0)
	v_add_f32_e32 v59, v59, v60
	v_fmamk_f32 v59, v59, 0x3a800000, v58
	v_mul_f32_e32 v60, 0x4b800000, v59
	v_cmp_gt_f32_e64 s[0:1], s10, v59
	s_nop 1
	v_cndmask_b32_e64 v59, v59, v60, s[0:1]
	v_rsq_f32_e32 v59, v59
	v_lshl_add_u64 v[60:61], v[48:49], 0, v[166:167]
	v_lshl_add_u64 v[48:49], v[48:49], 0, s[2:3]
	v_mul_f32_e32 v62, 0x45800000, v59
	v_cndmask_b32_e64 v62, v59, v62, s[0:1]
	v_mul_f32_e64 v28, v28, v62
	v_mul_f32_e64 v29, v29, v62
	v_mul_f32_e64 v30, v30, v62
	v_mul_f32_e64 v31, v31, v62
	v_mul_f32_e64 v64, v24, v62
	v_mul_f32_e64 v65, v25, v62
	v_mul_f32_e64 v66, v26, v62
	v_mul_f32_e64 v67, v27, v62
	v_mul_f32_e64 v26, v14, v30
	v_mul_f32_e64 v27, v15, v31
	v_mul_f32_e64 v24, v12, v28
	v_mul_f32_e64 v25, v13, v29
	v_mul_f32_e64 v20, v20, v62
	v_mul_f32_e64 v21, v21, v62
	v_mul_f32_e64 v22, v22, v62
	v_mul_f32_e64 v23, v23, v62
	v_mul_f32_e64 v16, v16, v62
	v_mul_f32_e64 v17, v17, v62
	v_mul_f32_e64 v18, v18, v62
	v_mul_f32_e64 v19, v19, v62
	global_store_dwordx4 v[60:61], v[24:27], off
	v_mul_f32_e64 v22, v6, v22
	v_mul_f32_e64 v23, v7, v23
	v_mul_f32_e64 v20, v4, v20
	v_mul_f32_e64 v21, v5, v21
	v_mul_f32_e64 v26, v10, v66
	v_mul_f32_e64 v27, v11, v67
	v_mul_f32_e64 v24, v8, v64
	v_mul_f32_e64 v25, v9, v65
	v_mul_f32_e64 v18, v2, v18
	v_mul_f32_e64 v19, v3, v19
	v_mul_f32_e64 v16, v0, v16
	v_mul_f32_e64 v17, v1, v17
	global_store_dwordx4 v[60:61], v[24:27], off offset:1024
	global_store_dwordx4 v[60:61], v[20:23], off offset:2048
	global_store_dwordx4 v[60:61], v[16:19], off offset:3072
	v_mov_b64_e32 v[24:25], v[40:41]
	v_mov_b64_e32 v[20:21], v[36:37]
	v_mov_b64_e32 v[16:17], v[32:33]
	v_mov_b64_e32 v[28:29], v[44:45]
	v_mov_b64_e32 v[18:19], v[34:35]
	v_mov_b64_e32 v[22:23], v[38:39]
	v_mov_b64_e32 v[26:27], v[42:43]
	v_mov_b64_e32 v[30:31], v[46:47]
	s_andn2_b64 exec, exec, s[4:5]
	s_cbranch_execz .LBB0_1054
